# grid barrier: arrivers at rank 3/4 and second-to-last of each XCD start an early L2 writeback (not waited for)
# speedup vs baseline: 1.0043x; 1.0043x over previous
; __device__ __forceinline__ unsigned xb_add(unsigned* p, unsigned v) { return __hip_atomic_fetch_add(p, v, __ATOMIC_RELAXED, __HIP_MEMORY_SCOPE_AGENT); }
; __device__ __forceinline__ void xcd_barrier(const XcdBarrier& b) {
;     ...
;         const unsigned old = xb_add(&bar[XB_XSUB(b.x)], 1u);
;         const unsigned gen = old / nloc;
;         if (old + 1u == (gen + 1u) * nloc) {
;             __builtin_amdgcn_fence(__ATOMIC_RELEASE, "agent");
.LBB0_134:
	v_readlane_b32 s4, v254, 9
	s_lshl_b32 s4, s4, 8
	v_readlane_b32 s6, v254, 7
	v_readlane_b32 s7, v254, 8
	s_add_u32 s4, s6, s4
	s_addc_u32 s5, s7, 0
	v_mov_b32_e32 v2, 0x1000
	v_mov_b32_e32 v4, 1
	global_atomic_add v4, v2, v4, s[4:5] offset:1024 sc0
	v_cvt_f32_u32_e32 v2, v3
	v_sub_u32_e32 v5, 0, v3
	v_rcp_iflag_f32_e32 v2, v2
	s_nop 0
	v_mul_f32_e32 v2, 0x4f7ffffe, v2
	v_cvt_u32_f32_e32 v2, v2
	v_mul_lo_u32 v5, v5, v2
	v_mul_hi_u32 v5, v2, v5
	v_add_u32_e32 v2, v2, v5
	s_waitcnt vmcnt(0)
	v_mul_hi_u32 v2, v4, v2
	v_mul_lo_u32 v5, v2, v3
	v_sub_u32_e32 v5, v4, v5
	v_add_u32_e32 v6, 1, v2
	v_cmp_ge_u32_e32 vcc, v5, v3
	v_add_u32_e32 v4, 1, v4
	s_nop 0
	v_cndmask_b32_e32 v2, v2, v6, vcc
	v_sub_u32_e32 v6, v5, v3
	v_cndmask_b32_e32 v5, v5, v6, vcc
	v_add_u32_e32 v6, 1, v2
	v_cmp_ge_u32_e32 vcc, v5, v3
	s_nop 1
	v_cndmask_b32_e32 v2, v2, v6, vcc
	v_mul_lo_u32 v5, v3, v2
	v_add_u32_e32 v3, v5, v3
	v_cmp_ne_u32_e32 vcc, v4, v3
	s_and_saveexec_b64 s[6:7], vcc
	s_xor_b64 s[6:7], exec, s[6:7]
	s_cbranch_execz .LBB0_148
	s_waitcnt lgkmcnt(0)
	v_sub_u32_e32 v12, v4, v5
	v_sub_u32_e32 v13, v3, v5
	v_lshrrev_b32_e32 v14, 2, v13
	v_sub_u32_e32 v14, v13, v14
	v_cmp_eq_u32_e32 vcc, v12, v14
	s_cbranch_vccnz .Lbwf_1
	v_add_u32_e32 v14, -1, v13
	v_cmp_eq_u32_e32 vcc, v12, v14
	s_cbranch_vccnz .Lbwf_1
	s_branch .Lbwn_1

; __device__ __forceinline__ unsigned xb_add(unsigned* p, unsigned v) { return __hip_atomic_fetch_add(p, v, __ATOMIC_RELAXED, __HIP_MEMORY_SCOPE_AGENT); }
; __device__ __forceinline__ void xcd_barrier(const XcdBarrier& b) {
;     ...
;         const unsigned old = xb_add(&bar[XB_XSUB(b.x)], 1u);
;         const unsigned gen = old / nloc;
;         if (old + 1u == (gen + 1u) * nloc) {
;             __builtin_amdgcn_fence(__ATOMIC_RELEASE, "agent");
.LBB0_3529:
	v_readlane_b32 s4, v254, 9
	s_lshl_b32 s4, s4, 8
	v_readlane_b32 s6, v254, 7
	v_readlane_b32 s7, v254, 8
	s_add_u32 s4, s6, s4
	s_addc_u32 s5, s7, 0
	v_mov_b32_e32 v1, 0x1000
	v_mov_b32_e32 v3, 1
	global_atomic_add v3, v1, v3, s[4:5] offset:1024 sc0
	v_cvt_f32_u32_e32 v1, v2
	v_sub_u32_e32 v4, 0, v2
	v_rcp_iflag_f32_e32 v1, v1
	s_nop 0
	v_mul_f32_e32 v1, 0x4f7ffffe, v1
	v_cvt_u32_f32_e32 v1, v1
	v_mul_lo_u32 v4, v4, v1
	v_mul_hi_u32 v4, v1, v4
	v_add_u32_e32 v1, v1, v4
	s_waitcnt vmcnt(0)
	v_mul_hi_u32 v1, v3, v1
	v_mul_lo_u32 v4, v1, v2
	v_sub_u32_e32 v4, v3, v4
	v_add_u32_e32 v5, 1, v1
	v_cmp_ge_u32_e32 vcc, v4, v2
	v_add_u32_e32 v3, 1, v3
	s_nop 0
	v_cndmask_b32_e32 v1, v1, v5, vcc
	v_sub_u32_e32 v5, v4, v2
	v_cndmask_b32_e32 v4, v4, v5, vcc
	v_add_u32_e32 v5, 1, v1
	v_cmp_ge_u32_e32 vcc, v4, v2
	s_nop 1
	v_cndmask_b32_e32 v1, v1, v5, vcc
	v_mul_lo_u32 v4, v2, v1
	v_add_u32_e32 v2, v4, v2
	v_cmp_ne_u32_e32 vcc, v3, v2
	s_and_saveexec_b64 s[6:7], vcc
	s_xor_b64 s[6:7], exec, s[6:7]
	s_cbranch_execz .LBB0_3543
	s_waitcnt lgkmcnt(0)
	v_sub_u32_e32 v12, v3, v4
	v_sub_u32_e32 v13, v2, v4
	v_lshrrev_b32_e32 v14, 2, v13
	v_sub_u32_e32 v14, v13, v14
	v_cmp_eq_u32_e32 vcc, v12, v14
	s_cbranch_vccnz .Lbwf_22
	v_add_u32_e32 v14, -1, v13
	v_cmp_eq_u32_e32 vcc, v12, v14
	s_cbranch_vccnz .Lbwf_22
	s_branch .Lbwn_22
